# out-proj GEMM unit loop: next-unit decode moved from the unit head into the second load segment of the peeled K iteration
# baseline (speedup 1.0000x reference)
.LBB0_852:
	s_add_u32 s82, s28, 0x100
	s_addc_u32 s83, s29, 0
	s_add_u32 s28, s30, 0x40080
	s_addc_u32 s29, s31, 0
	s_mov_b32 s85, -2
	s_waitcnt lgkmcnt(0)
	s_add_u32 s30, s28, 0xfffc0080
	s_addc_u32 s31, s29, -1
	s_add_i32 s86, 0, 0x10000
	s_cmp_eq_u32 s85, 12
	s_cselect_b32 s35, s23, s31
	s_cselect_b32 s34, s61, s30
	s_cselect_b32 s31, s21, s83
	s_cselect_b32 s30, s68, s82
	s_add_i32 s88, 0, 0x14000
	v_add_u32_e32 v124, s86, v248
	v_add_u32_e32 v156, s88, v248
	ds_read_b128 v[88:91], v124
	ds_read_b128 v[100:103], v124 offset:1024
	ds_read_b128 v[112:115], v124 offset:2048
	ds_read_b128 v[124:127], v124 offset:3072
	ds_read_b128 v[136:139], v156
	ds_read_b128 v[140:143], v156 offset:1024
	ds_read_b128 v[148:151], v156 offset:2048
	ds_read_b128 v[156:159], v156 offset:3072
	v_lshl_add_u64 v[212:213], s[28:29], 0, v[210:211]
	s_add_i32 m0, s47, 0xc000
	ds_read_b128 v[160:163], v250
	ds_read_b128 v[164:167], v250 offset:1024
	ds_read_b128 v[168:171], v250 offset:2048
	ds_read_b128 v[172:175], v250 offset:3072
	ds_read_b128 v[176:179], v250 offset:4096
	ds_read_b128 v[180:183], v250 offset:5120
	ds_read_b128 v[184:187], v250 offset:6144
	ds_read_b128 v[188:191], v250 offset:7168
	global_load_lds_dwordx4 v[212:213], off
	v_lshl_add_u64 v[212:213], s[28:29], 0, v[208:209]
	s_add_i32 m0, s47, 0xe000
	s_nop 0
	global_load_lds_dwordx4 v[212:213], off
	s_waitcnt vmcnt(8)
	s_waitcnt lgkmcnt(0)
	s_barrier
	s_setprio 1
	s_waitcnt lgkmcnt(0)
	v_mfma_f32_16x16x32_bf16 v[152:155], v[88:91], v[160:163], 0
	v_mfma_f32_16x16x32_bf16 v[144:147], v[112:115], v[160:163], 0
	v_mfma_f32_16x16x32_bf16 v[120:123], v[88:91], v[168:171], 0
	v_mfma_f32_16x16x32_bf16 v[116:119], v[112:115], v[168:171], 0
	v_mfma_f32_16x16x32_bf16 v[96:99], v[88:91], v[176:179], 0
	v_mfma_f32_16x16x32_bf16 v[92:95], v[112:115], v[176:179], 0
	v_mfma_f32_16x16x32_bf16 v[76:79], v[88:91], v[184:187], 0
	v_mfma_f32_16x16x32_bf16 v[72:75], v[112:115], v[184:187], 0
	v_mfma_f32_16x16x32_bf16 v[152:155], v[100:103], v[164:167], v[152:155]
	v_mfma_f32_16x16x32_bf16 v[144:147], v[124:127], v[164:167], v[144:147]
	v_mfma_f32_16x16x32_bf16 v[120:123], v[100:103], v[172:175], v[120:123]
	v_mfma_f32_16x16x32_bf16 v[116:119], v[124:127], v[172:175], v[116:119]
	v_mfma_f32_16x16x32_bf16 v[96:99], v[100:103], v[180:183], v[96:99]
	v_mfma_f32_16x16x32_bf16 v[92:95], v[124:127], v[180:183], v[92:95]
	v_mfma_f32_16x16x32_bf16 v[76:79], v[100:103], v[188:191], v[76:79]
	v_mfma_f32_16x16x32_bf16 v[72:75], v[124:127], v[188:191], v[72:75]
	s_setprio 0
	s_setprio 1
	v_mfma_f32_16x16x32_bf16 v[132:135], v[136:139], v[160:163], 0
	v_mfma_f32_16x16x32_bf16 v[128:131], v[148:151], v[160:163], 0
	v_mfma_f32_16x16x32_bf16 v[108:111], v[136:139], v[168:171], 0
	v_mfma_f32_16x16x32_bf16 v[104:107], v[148:151], v[168:171], 0
	v_mfma_f32_16x16x32_bf16 v[84:87], v[136:139], v[176:179], 0
	v_mfma_f32_16x16x32_bf16 v[80:83], v[148:151], v[176:179], 0
	v_mfma_f32_16x16x32_bf16 v[68:71], v[136:139], v[184:187], 0
	v_mfma_f32_16x16x32_bf16 v[64:67], v[148:151], v[184:187], 0
	v_mfma_f32_16x16x32_bf16 v[132:135], v[140:143], v[164:167], v[132:135]
	v_mfma_f32_16x16x32_bf16 v[128:131], v[156:159], v[164:167], v[128:131]
	v_mfma_f32_16x16x32_bf16 v[108:111], v[140:143], v[172:175], v[108:111]
	v_mfma_f32_16x16x32_bf16 v[104:107], v[156:159], v[172:175], v[104:107]
	v_mfma_f32_16x16x32_bf16 v[84:87], v[140:143], v[180:183], v[84:87]
	v_mfma_f32_16x16x32_bf16 v[80:83], v[156:159], v[180:183], v[80:83]
	v_mfma_f32_16x16x32_bf16 v[68:71], v[140:143], v[188:191], v[68:71]
	v_mfma_f32_16x16x32_bf16 v[64:67], v[156:159], v[188:191], v[64:67]
	s_setprio 0
	s_barrier
	s_add_i32 s86, s86, s46
	v_lshl_add_u64 v[212:213], s[30:31], 0, v[192:193]
	s_mov_b32 m0, s86
	ds_read_b128 v[160:163], v250 offset:16384
	ds_read_b128 v[164:167], v250 offset:17408
	ds_read_b128 v[168:171], v250 offset:18432
	ds_read_b128 v[172:175], v250 offset:19456
	ds_read_b128 v[176:179], v250 offset:20480
	ds_read_b128 v[180:183], v250 offset:21504
	ds_read_b128 v[184:187], v250 offset:22528
	ds_read_b128 v[188:191], v250 offset:23552
	global_load_lds_dwordx4 v[212:213], off
	s_add_i32 m0, s86, 0x2000
	s_add_u32 s86, s30, 0x40000
	v_lshl_add_u64 v[214:215], s[30:31], 0, v[202:203]
	s_addc_u32 s87, s31, 0
	s_add_i32 s88, s88, s46
	global_load_lds_dwordx4 v[214:215], off
	v_lshl_add_u64 v[216:217], s[86:87], 0, v[192:193]
	s_mov_b32 m0, s88
	v_lshl_add_u64 v[218:219], s[34:35], 0, v[204:205]
	global_load_lds_dwordx4 v[216:217], off
	v_lshl_add_u64 v[216:217], s[86:87], 0, v[202:203]
	s_add_i32 m0, s88, 0x2000
	s_nop 0
	global_load_lds_dwordx4 v[216:217], off
	v_lshl_add_u64 v[216:217], s[34:35], 0, v[206:207]
	s_mov_b32 m0, s47
	s_nop 0
	global_load_lds_dwordx4 v[216:217], off
	s_mov_b32 m0, s48
	s_nop 0
	global_load_lds_dwordx4 v[218:219], off
	s_add_i32 s56, s56, 1
	s_mul_i32 s8, s56, s43
	s_mul_hi_u32 s9, s56, s42
	s_add_i32 s9, s9, s8
	s_mul_i32 s8, s56, s42
	s_add_u32 s24, s8, s2
	s_addc_u32 s25, s9, s41
	v_cmp_gt_i64_e32 vcc, s[24:25], v[196:197]
	v_cmp_lt_i64_e64 s[8:9], s[24:25], v[194:195]
	s_cbranch_vccnz .LBB0_858
	s_ashr_i32 s20, s24, 31
	s_lshr_b32 s20, s20, 29
	s_add_i32 s22, s24, s20
	s_and_b32 s20, s22, -8
	s_sub_i32 s23, s24, s20
	s_cmp_gt_i32 s23, -1
	s_mov_b64 s[20:21], -1
	s_cbranch_scc0 .LBB0_855
	s_lshl_b32 s24, s23, 7
	s_mov_b64 s[20:21], 0

.LBB0_857:
	s_ashr_i32 s20, s22, 3
	s_add_i32 s20, s24, s20
	s_ashr_i32 s21, s20, 31
	s_lshr_b32 s21, s21, 27
	s_add_i32 s21, s20, s21
	s_ashr_i32 s22, s21, 5
	s_lshl_b32 s22, s22, 3
	s_sub_i32 s23, 0x100, s22
	s_min_i32 s23, s23, 8
	s_abs_i32 s24, s23
	v_cvt_f32_u32_e32 v0, s24
	s_sub_i32 s26, 0, s24
	s_andn2_b32 s21, s21, 31
	s_sub_i32 s21, s20, s21
	v_rcp_iflag_f32_e32 v0, v0
	s_abs_i32 s20, s21
	s_xor_b32 s25, s21, s23
	s_ashr_i32 s25, s25, 31
	v_mul_f32_e32 v0, 0x4f7ffffe, v0
	v_cvt_u32_f32_e32 v0, v0
	s_nop 0
	v_readfirstlane_b32 s27, v0
	s_mul_i32 s26, s26, s27
	s_mul_hi_u32 s26, s27, s26
	s_add_i32 s27, s27, s26
	s_mul_hi_u32 s26, s20, s27
	s_mul_i32 s27, s26, s24
	s_sub_i32 s20, s20, s27
	s_add_i32 s32, s26, 1
	s_sub_i32 s27, s20, s24
	s_cmp_ge_u32 s20, s24
	s_cselect_b32 s26, s32, s26
	s_cselect_b32 s20, s27, s20
	s_add_i32 s27, s26, 1
	s_cmp_ge_u32 s20, s24
	s_cselect_b32 s20, s27, s26
	s_xor_b32 s20, s20, s25
	s_sub_i32 s20, s20, s25
	s_mul_i32 s23, s20, s23
	s_sub_i32 s21, s21, s23
	s_add_i32 s22, s22, s21
.LBB0_858:
	s_ashr_i32 s23, s22, 31
	s_lshl_b64 s[24:25], s[22:23], 19
	s_add_u32 s24, s36, s24
	s_addc_u32 s25, s37, s25
	s_and_b64 s[26:27], s[8:9], exec
	s_cselect_b32 s23, s25, s35
	s_cselect_b32 s61, s24, s34
	s_ashr_i32 s21, s20, 31
	s_lshl_b64 s[26:27], s[20:21], 19
	s_add_u32 s26, s38, s26
	s_addc_u32 s27, s39, s27
	s_and_b64 s[100:101], s[8:9], exec
	s_cselect_b32 s21, s27, s83
	s_cselect_b32 s68, s26, s82
	s_waitcnt vmcnt(8)
	s_waitcnt lgkmcnt(0)
	s_barrier
	s_setprio 1
	s_waitcnt lgkmcnt(0)
	v_mfma_f32_16x16x32_bf16 v[60:63], v[88:91], v[160:163], 0
	v_mfma_f32_16x16x32_bf16 v[56:59], v[112:115], v[160:163], 0
	v_mfma_f32_16x16x32_bf16 v[44:47], v[88:91], v[168:171], 0
	v_mfma_f32_16x16x32_bf16 v[40:43], v[112:115], v[168:171], 0
	v_mfma_f32_16x16x32_bf16 v[28:31], v[88:91], v[176:179], 0
	v_mfma_f32_16x16x32_bf16 v[24:27], v[112:115], v[176:179], 0
	v_mfma_f32_16x16x32_bf16 v[12:15], v[88:91], v[184:187], 0
	v_mfma_f32_16x16x32_bf16 v[8:11], v[112:115], v[184:187], 0
	v_mfma_f32_16x16x32_bf16 v[60:63], v[100:103], v[164:167], v[60:63]
	v_mfma_f32_16x16x32_bf16 v[56:59], v[124:127], v[164:167], v[56:59]
	v_mfma_f32_16x16x32_bf16 v[44:47], v[100:103], v[172:175], v[44:47]
	v_mfma_f32_16x16x32_bf16 v[40:43], v[124:127], v[172:175], v[40:43]
	v_mfma_f32_16x16x32_bf16 v[28:31], v[100:103], v[180:183], v[28:31]
	v_mfma_f32_16x16x32_bf16 v[24:27], v[124:127], v[180:183], v[24:27]
	v_mfma_f32_16x16x32_bf16 v[12:15], v[100:103], v[188:191], v[12:15]
	v_mfma_f32_16x16x32_bf16 v[8:11], v[124:127], v[188:191], v[8:11]
	s_setprio 0
	s_setprio 1
	v_mfma_f32_16x16x32_bf16 v[52:55], v[136:139], v[160:163], 0
	v_mfma_f32_16x16x32_bf16 v[48:51], v[148:151], v[160:163], 0
	v_mfma_f32_16x16x32_bf16 v[36:39], v[136:139], v[168:171], 0
	v_mfma_f32_16x16x32_bf16 v[32:35], v[148:151], v[168:171], 0
	v_mfma_f32_16x16x32_bf16 v[20:23], v[136:139], v[176:179], 0
	v_mfma_f32_16x16x32_bf16 v[16:19], v[148:151], v[176:179], 0
	v_mfma_f32_16x16x32_bf16 v[4:7], v[136:139], v[184:187], 0
	v_mfma_f32_16x16x32_bf16 v[0:3], v[148:151], v[184:187], 0
	v_mfma_f32_16x16x32_bf16 v[52:55], v[140:143], v[164:167], v[52:55]
	v_mfma_f32_16x16x32_bf16 v[48:51], v[156:159], v[164:167], v[48:51]
	v_mfma_f32_16x16x32_bf16 v[36:39], v[140:143], v[172:175], v[36:39]
	v_mfma_f32_16x16x32_bf16 v[32:35], v[156:159], v[172:175], v[32:35]
	v_mfma_f32_16x16x32_bf16 v[20:23], v[140:143], v[180:183], v[20:23]
	v_mfma_f32_16x16x32_bf16 v[16:19], v[156:159], v[180:183], v[16:19]
	v_mfma_f32_16x16x32_bf16 v[4:7], v[140:143], v[188:191], v[4:7]
	v_mfma_f32_16x16x32_bf16 v[0:3], v[156:159], v[188:191], v[0:3]
	s_setprio 0
	s_barrier
	s_add_i32 s86, 0, 0x18000
	s_add_i32 s87, 0, 0x1c000
	v_add_u32_e32 v124, s86, v248
	v_add_u32_e32 v156, s87, v248
	ds_read_b128 v[88:91], v124
	ds_read_b128 v[100:103], v124 offset:1024
	ds_read_b128 v[112:115], v124 offset:2048
	ds_read_b128 v[124:127], v124 offset:3072
	ds_read_b128 v[136:139], v156
	ds_read_b128 v[140:143], v156 offset:1024
	ds_read_b128 v[148:151], v156 offset:2048
	ds_read_b128 v[156:159], v156 offset:3072
	s_add_u32 s34, s34, 0x40000
	s_addc_u32 s35, s35, 0
	s_mov_b32 m0, s49
	v_lshl_add_u64 v[220:221], s[34:35], 0, v[206:207]
	ds_read_b128 v[160:163], v250 offset:32768
	ds_read_b128 v[164:167], v250 offset:33792
	ds_read_b128 v[168:171], v250 offset:34816
	ds_read_b128 v[172:175], v250 offset:35840
	ds_read_b128 v[176:179], v250 offset:36864
	ds_read_b128 v[180:183], v250 offset:37888
	ds_read_b128 v[184:187], v250 offset:38912
	ds_read_b128 v[188:191], v250 offset:39936
	global_load_lds_dwordx4 v[220:221], off
	v_lshl_add_u64 v[220:221], s[34:35], 0, v[204:205]
	s_mov_b32 m0, s50
	s_nop 0
	global_load_lds_dwordx4 v[220:221], off
	s_waitcnt vmcnt(8)
	s_waitcnt lgkmcnt(0)
	s_barrier
	s_setprio 1
	s_waitcnt lgkmcnt(0)
	v_mfma_f32_16x16x32_bf16 v[152:155], v[88:91], v[160:163], v[152:155]
	v_mfma_f32_16x16x32_bf16 v[144:147], v[112:115], v[160:163], v[144:147]
	v_mfma_f32_16x16x32_bf16 v[120:123], v[88:91], v[168:171], v[120:123]
	v_mfma_f32_16x16x32_bf16 v[116:119], v[112:115], v[168:171], v[116:119]
	v_mfma_f32_16x16x32_bf16 v[96:99], v[88:91], v[176:179], v[96:99]
	v_mfma_f32_16x16x32_bf16 v[92:95], v[112:115], v[176:179], v[92:95]
	v_mfma_f32_16x16x32_bf16 v[76:79], v[88:91], v[184:187], v[76:79]
	v_mfma_f32_16x16x32_bf16 v[72:75], v[112:115], v[184:187], v[72:75]
	v_mfma_f32_16x16x32_bf16 v[152:155], v[100:103], v[164:167], v[152:155]
	v_mfma_f32_16x16x32_bf16 v[144:147], v[124:127], v[164:167], v[144:147]
	v_mfma_f32_16x16x32_bf16 v[120:123], v[100:103], v[172:175], v[120:123]
	v_mfma_f32_16x16x32_bf16 v[116:119], v[124:127], v[172:175], v[116:119]
	v_mfma_f32_16x16x32_bf16 v[96:99], v[100:103], v[180:183], v[96:99]
	v_mfma_f32_16x16x32_bf16 v[92:95], v[124:127], v[180:183], v[92:95]
	v_mfma_f32_16x16x32_bf16 v[76:79], v[100:103], v[188:191], v[76:79]
	v_mfma_f32_16x16x32_bf16 v[72:75], v[124:127], v[188:191], v[72:75]
	s_setprio 0
	s_setprio 1
	v_mfma_f32_16x16x32_bf16 v[132:135], v[136:139], v[160:163], v[132:135]
	v_mfma_f32_16x16x32_bf16 v[128:131], v[148:151], v[160:163], v[128:131]
	v_mfma_f32_16x16x32_bf16 v[108:111], v[136:139], v[168:171], v[108:111]
	v_mfma_f32_16x16x32_bf16 v[104:107], v[148:151], v[168:171], v[104:107]
	v_mfma_f32_16x16x32_bf16 v[84:87], v[136:139], v[176:179], v[84:87]
	v_mfma_f32_16x16x32_bf16 v[80:83], v[148:151], v[176:179], v[80:83]
	v_mfma_f32_16x16x32_bf16 v[68:71], v[136:139], v[184:187], v[68:71]
	v_mfma_f32_16x16x32_bf16 v[64:67], v[148:151], v[184:187], v[64:67]
	v_mfma_f32_16x16x32_bf16 v[132:135], v[140:143], v[164:167], v[132:135]
	v_mfma_f32_16x16x32_bf16 v[128:131], v[156:159], v[164:167], v[128:131]
	v_mfma_f32_16x16x32_bf16 v[108:111], v[140:143], v[172:175], v[108:111]
	v_mfma_f32_16x16x32_bf16 v[104:107], v[156:159], v[172:175], v[104:107]
	v_mfma_f32_16x16x32_bf16 v[84:87], v[140:143], v[180:183], v[84:87]
	v_mfma_f32_16x16x32_bf16 v[80:83], v[156:159], v[180:183], v[80:83]
	v_mfma_f32_16x16x32_bf16 v[68:71], v[140:143], v[188:191], v[68:71]
	v_mfma_f32_16x16x32_bf16 v[64:67], v[156:159], v[188:191], v[64:67]
	s_setprio 0
	s_barrier
	s_add_i32 s34, s86, s46
	v_lshl_add_u64 v[212:213], v[212:213], 0, s[76:77]
	s_mov_b32 m0, s34
	ds_read_b128 v[160:163], v250 offset:49152
	ds_read_b128 v[164:167], v250 offset:50176
	ds_read_b128 v[168:171], v250 offset:51200
	ds_read_b128 v[172:175], v250 offset:52224
	ds_read_b128 v[176:179], v250 offset:53248
	ds_read_b128 v[180:183], v250 offset:54272
	ds_read_b128 v[184:187], v250 offset:55296
	ds_read_b128 v[188:191], v250 offset:56320
	global_load_lds_dwordx4 v[212:213], off
	s_add_i32 m0, s34, 0x2000
	s_add_u32 s30, s30, 0x40080
	v_lshl_add_u64 v[212:213], v[214:215], 0, s[76:77]
	s_addc_u32 s31, s31, 0
	s_add_i32 s34, s87, s46
	global_load_lds_dwordx4 v[212:213], off
	v_lshl_add_u64 v[212:213], s[30:31], 0, v[192:193]
	s_mov_b32 m0, s34
	s_nop 0
	global_load_lds_dwordx4 v[212:213], off
	v_lshl_add_u64 v[212:213], s[30:31], 0, v[202:203]
	s_add_i32 m0, s34, 0x2000
	s_nop 0
	global_load_lds_dwordx4 v[212:213], off
	v_lshl_add_u64 v[212:213], v[216:217], 0, s[76:77]
	s_mov_b32 m0, s54
	s_nop 0
	global_load_lds_dwordx4 v[212:213], off
	v_lshl_add_u64 v[212:213], v[218:219], 0, s[76:77]
	s_mov_b32 m0, s55
	s_nop 0
	global_load_lds_dwordx4 v[212:213], off
	s_waitcnt vmcnt(8)
	s_waitcnt lgkmcnt(0)
	s_barrier
	s_setprio 1
	s_waitcnt lgkmcnt(0)
	v_mfma_f32_16x16x32_bf16 v[60:63], v[88:91], v[160:163], v[60:63]
	v_mfma_f32_16x16x32_bf16 v[56:59], v[112:115], v[160:163], v[56:59]
	v_mfma_f32_16x16x32_bf16 v[44:47], v[88:91], v[168:171], v[44:47]
	v_mfma_f32_16x16x32_bf16 v[40:43], v[112:115], v[168:171], v[40:43]
	v_mfma_f32_16x16x32_bf16 v[28:31], v[88:91], v[176:179], v[28:31]
	v_mfma_f32_16x16x32_bf16 v[24:27], v[112:115], v[176:179], v[24:27]
	v_mfma_f32_16x16x32_bf16 v[12:15], v[88:91], v[184:187], v[12:15]
	v_mfma_f32_16x16x32_bf16 v[8:11], v[112:115], v[184:187], v[8:11]
	v_mfma_f32_16x16x32_bf16 v[60:63], v[100:103], v[164:167], v[60:63]
	v_mfma_f32_16x16x32_bf16 v[56:59], v[124:127], v[164:167], v[56:59]
	v_mfma_f32_16x16x32_bf16 v[44:47], v[100:103], v[172:175], v[44:47]
	v_mfma_f32_16x16x32_bf16 v[40:43], v[124:127], v[172:175], v[40:43]
	v_mfma_f32_16x16x32_bf16 v[28:31], v[100:103], v[180:183], v[28:31]
	v_mfma_f32_16x16x32_bf16 v[24:27], v[124:127], v[180:183], v[24:27]
	v_mfma_f32_16x16x32_bf16 v[12:15], v[100:103], v[188:191], v[12:15]
	v_mfma_f32_16x16x32_bf16 v[8:11], v[124:127], v[188:191], v[8:11]
	s_setprio 0
	s_setprio 1
	v_mfma_f32_16x16x32_bf16 v[52:55], v[136:139], v[160:163], v[52:55]
	v_mfma_f32_16x16x32_bf16 v[48:51], v[148:151], v[160:163], v[48:51]
	v_mfma_f32_16x16x32_bf16 v[36:39], v[136:139], v[168:171], v[36:39]
	v_mfma_f32_16x16x32_bf16 v[32:35], v[148:151], v[168:171], v[32:35]
	v_mfma_f32_16x16x32_bf16 v[20:23], v[136:139], v[176:179], v[20:23]
	v_mfma_f32_16x16x32_bf16 v[16:19], v[148:151], v[176:179], v[16:19]
	v_mfma_f32_16x16x32_bf16 v[4:7], v[136:139], v[184:187], v[4:7]
	v_mfma_f32_16x16x32_bf16 v[0:3], v[148:151], v[184:187], v[0:3]
	v_mfma_f32_16x16x32_bf16 v[52:55], v[140:143], v[164:167], v[52:55]
	v_mfma_f32_16x16x32_bf16 v[48:51], v[156:159], v[164:167], v[48:51]
	v_mfma_f32_16x16x32_bf16 v[36:39], v[140:143], v[172:175], v[36:39]
	v_mfma_f32_16x16x32_bf16 v[32:35], v[156:159], v[172:175], v[32:35]
	v_mfma_f32_16x16x32_bf16 v[20:23], v[140:143], v[180:183], v[20:23]
	v_mfma_f32_16x16x32_bf16 v[16:19], v[156:159], v[180:183], v[16:19]
	v_mfma_f32_16x16x32_bf16 v[4:7], v[140:143], v[188:191], v[4:7]
	v_mfma_f32_16x16x32_bf16 v[0:3], v[156:159], v[188:191], v[0:3]
	s_setprio 0
	s_barrier
	s_add_i32 s85, s85, 2
	s_add_u32 s82, s82, 0x100
	s_addc_u32 s83, s83, 0
	s_add_u32 s28, s28, 0x100
	s_addc_u32 s29, s29, 0
	s_cmp_gt_u32 s85, 13
